# G1 swiglu epilogue chains regenerated 4-way interleaved (no hazard nops), same math and order per element
# baseline (speedup 1.0000x reference)
; __device__ __forceinline__ unsigned cvt_pk_bf16(float lo, float hi) { unsigned r; asm volatile("v_cvt_pk_bf16_f32 %0, %1, %2" : "=v"(r) : "v"(lo), "v"(hi)); return r; }
;     __device__ __forceinline__ void operator()(const f32x4 (&acc)[2][2][4][2], const Unit& u, int wr, int wc, int fr, int fq) const {
;         const int row0 = u.pm * BM + wr * 64 + fr, col0 = u.pn * HALF + wc * 32 + 8 * fq;
;         float rsv[2][4]; row_rs8(rsv, part, row0, fq);
; #pragma unroll
;         for (int ai = 0; ai < 2; ++ai)
; #pragma unroll
;             for (int m = 0; m < 4; ++m) { const int row = row0 + ai * HALF + m * 16; const float rs = rsv[ai][m], c1 = rs * -1.4426950408889634f, rs2 = rs * rs;
;                 u32x4 w;
; #pragma unroll
;                 for (int n = 0; n < 2; ++n)
; #pragma unroll
;                     for (int h = 0; h < 2; ++h) { const f32x2 g = (f32x2){acc[ai][0][m][n][2 * h], acc[ai][0][m][n][2 * h + 1]}, up = (f32x2){acc[ai][1][m][n][2 * h], acc[ai][1][m][n][2 * h + 1]};
;                         const f32x2 t = g * c1; f32x2 d = (f32x2){__builtin_amdgcn_exp2f(t[0]), __builtin_amdgcn_exp2f(t[1])} + 1.0f;
;                         const f32x2 r = (f32x2){__builtin_amdgcn_rcpf(d[0]), __builtin_amdgcn_rcpf(d[1])}; const f32x2 o = (g * up) * (r * rs2);
;                         w[2 * n + h] = cvt_pk_bf16(o[0], o[1]); }
;                 __builtin_nontemporal_store(w, (u32x4*)(H + (size_t)row * ldh + col0)); }
.LBB0_201:
	v_lshl_add_u32 v178, s59, 8, v190
	v_lshlrev_b32_e32 v194, 2, v190
	v_add_u32_e32 v194, 0x20000, v194
	ds_read_b32 v171, v194
	ds_read_b32 v165, v194 offset:64
	ds_read_b32 v145, v194 offset:128
	ds_read_b32 v144, v194 offset:192
	ds_read_b32 v137, v194 offset:512
	ds_read_b32 v136, v194 offset:576
	ds_read_b32 v129, v194 offset:640
	ds_read_b32 v128, v194 offset:704
	v_or_b32_e32 v176, 16, v178
	v_or_b32_e32 v174, 32, v178
	v_or_b32_e32 v172, 48, v178
	v_add_u32_e32 v170, 0x80, v178
	v_add_u32_e32 v168, 0x90, v178
	v_add_u32_e32 v166, 0xa0, v178
	v_add_u32_e32 v164, 0xb0, v178
	v_lshl_or_b32 v186, s3, 7, v192
	v_ashrrev_i32_e32 v187, 31, v186
	v_pk_mul_f32 v[120:121], v[124:125], v[120:121]
	v_pk_mul_f32 v[122:123], v[126:127], v[122:123]
	v_pk_mul_f32 v[118:119], v[114:115], v[118:119]
	v_pk_mul_f32 v[104:105], v[108:109], v[104:105]
	v_pk_mul_f32 v[106:107], v[110:111], v[106:107]
	v_pk_mul_f32 v[102:103], v[98:99], v[102:103]
	v_pk_mul_f32 v[88:89], v[92:93], v[88:89]
	v_pk_mul_f32 v[90:91], v[94:95], v[90:91]
	v_pk_mul_f32 v[86:87], v[82:83], v[86:87]
	v_pk_mul_f32 v[72:73], v[76:77], v[72:73]
	v_pk_mul_f32 v[74:75], v[78:79], v[74:75]
	v_pk_mul_f32 v[70:71], v[66:67], v[70:71]
	v_pk_mul_f32 v[56:57], v[60:61], v[56:57]
	v_pk_mul_f32 v[58:59], v[62:63], v[58:59]
	v_pk_mul_f32 v[54:55], v[50:51], v[54:55]
	v_pk_mul_f32 v[40:41], v[44:45], v[40:41]
	v_pk_mul_f32 v[42:43], v[46:47], v[42:43]
	v_pk_mul_f32 v[38:39], v[34:35], v[38:39]
	v_pk_mul_f32 v[24:25], v[28:29], v[24:25]
	v_pk_mul_f32 v[26:27], v[30:31], v[26:27]
	v_pk_mul_f32 v[22:23], v[18:19], v[22:23]
	v_pk_mul_f32 v[8:9], v[12:13], v[8:9]
	v_pk_mul_f32 v[10:11], v[14:15], v[10:11]
	v_pk_mul_f32 v[0:1], v[4:5], v[0:1]
	v_pk_mul_f32 v[2:3], v[6:7], v[2:3]
	s_waitcnt lgkmcnt(0)
	s_andn2_b64 vcc, exec, s[4:5]
	v_mov_b64_e32 v[224:225], s[10:11]
	v_lshlrev_b64 v[226:227], 1, v[186:187]
	v_mul_f32_e32 v216, 0xbfb8aa3b, v171
	v_mul_f32_e32 v218, v171, v171
	v_pk_mul_f32 v[194:195], v[124:125], v[216:217] op_sel_hi:[1,0]
	v_pk_mul_f32 v[196:197], v[126:127], v[216:217] op_sel_hi:[1,0]
	v_pk_mul_f32 v[198:199], v[112:113], v[216:217] op_sel_hi:[1,0]
	v_pk_mul_f32 v[200:201], v[114:115], v[216:217] op_sel_hi:[1,0]
	v_pk_mul_f32 v[116:117], v[112:113], v[116:117]
	v_exp_f32_e32 v194, v194
	v_exp_f32_e32 v195, v195
	v_exp_f32_e32 v196, v196
	v_exp_f32_e32 v197, v197
	v_exp_f32_e32 v198, v198
	v_exp_f32_e32 v199, v199
	v_exp_f32_e32 v200, v200
	v_exp_f32_e32 v201, v201
	v_pk_add_f32 v[194:195], v[194:195], 1.0 op_sel_hi:[1,0]
	v_pk_add_f32 v[196:197], v[196:197], 1.0 op_sel_hi:[1,0]
	v_pk_add_f32 v[198:199], v[198:199], 1.0 op_sel_hi:[1,0]
	v_pk_add_f32 v[200:201], v[200:201], 1.0 op_sel_hi:[1,0]
	v_rcp_f32_e32 v194, v194
	v_rcp_f32_e32 v195, v195
	v_rcp_f32_e32 v196, v196
	v_rcp_f32_e32 v197, v197
	v_rcp_f32_e32 v198, v198
	v_rcp_f32_e32 v199, v199
	v_rcp_f32_e32 v200, v200
	v_rcp_f32_e32 v201, v201
	v_pk_mul_f32 v[194:195], v[218:219], v[194:195] op_sel_hi:[0,1]
	v_pk_mul_f32 v[196:197], v[218:219], v[196:197] op_sel_hi:[0,1]
	v_pk_mul_f32 v[198:199], v[218:219], v[198:199] op_sel_hi:[0,1]
	v_pk_mul_f32 v[200:201], v[218:219], v[200:201] op_sel_hi:[0,1]
	v_pk_mul_f32 v[120:121], v[120:121], v[194:195]
	v_pk_mul_f32 v[122:123], v[122:123], v[196:197]
	v_pk_mul_f32 v[116:117], v[116:117], v[198:199]
	v_pk_mul_f32 v[118:119], v[118:119], v[200:201]
	v_mad_i64_i32 v[230:231], s[6:7], v178, s25, v[224:225]
	v_cvt_pk_bf16_f32 v120, v120, v121
	v_cvt_pk_bf16_f32 v121, v122, v123
	v_cvt_pk_bf16_f32 v122, v116, v117
	v_cvt_pk_bf16_f32 v123, v118, v119
	v_lshl_add_u64 v[230:231], v[230:231], 0, v[226:227]
	global_store_dwordx4 v[230:231], v[120:123], off nt
	v_mul_f32_e32 v216, 0xbfb8aa3b, v165
	v_mul_f32_e32 v218, v165, v165
	v_pk_mul_f32 v[194:195], v[108:109], v[216:217] op_sel_hi:[1,0]
	v_pk_mul_f32 v[196:197], v[110:111], v[216:217] op_sel_hi:[1,0]
	v_pk_mul_f32 v[198:199], v[96:97], v[216:217] op_sel_hi:[1,0]
	v_pk_mul_f32 v[200:201], v[98:99], v[216:217] op_sel_hi:[1,0]
	v_pk_mul_f32 v[100:101], v[96:97], v[100:101]
	v_exp_f32_e32 v194, v194
	v_exp_f32_e32 v195, v195
	v_exp_f32_e32 v196, v196
	v_exp_f32_e32 v197, v197
	v_exp_f32_e32 v198, v198
	v_exp_f32_e32 v199, v199
	v_exp_f32_e32 v200, v200
	v_exp_f32_e32 v201, v201
	v_pk_add_f32 v[194:195], v[194:195], 1.0 op_sel_hi:[1,0]
	v_pk_add_f32 v[196:197], v[196:197], 1.0 op_sel_hi:[1,0]
	v_pk_add_f32 v[198:199], v[198:199], 1.0 op_sel_hi:[1,0]
	v_pk_add_f32 v[200:201], v[200:201], 1.0 op_sel_hi:[1,0]
	v_rcp_f32_e32 v194, v194
	v_rcp_f32_e32 v195, v195
	v_rcp_f32_e32 v196, v196
	v_rcp_f32_e32 v197, v197
	v_rcp_f32_e32 v198, v198
	v_rcp_f32_e32 v199, v199
	v_rcp_f32_e32 v200, v200
	v_rcp_f32_e32 v201, v201
	v_pk_mul_f32 v[194:195], v[218:219], v[194:195] op_sel_hi:[0,1]
	v_pk_mul_f32 v[196:197], v[218:219], v[196:197] op_sel_hi:[0,1]
	v_pk_mul_f32 v[198:199], v[218:219], v[198:199] op_sel_hi:[0,1]
	v_pk_mul_f32 v[200:201], v[218:219], v[200:201] op_sel_hi:[0,1]
	v_pk_mul_f32 v[104:105], v[104:105], v[194:195]
	v_pk_mul_f32 v[106:107], v[106:107], v[196:197]
	v_pk_mul_f32 v[100:101], v[100:101], v[198:199]
	v_pk_mul_f32 v[102:103], v[102:103], v[200:201]
	v_mad_i64_i32 v[230:231], s[6:7], v176, s25, v[224:225]
	v_cvt_pk_bf16_f32 v104, v104, v105
	v_cvt_pk_bf16_f32 v105, v106, v107
	v_cvt_pk_bf16_f32 v106, v100, v101
	v_cvt_pk_bf16_f32 v107, v102, v103
	v_lshl_add_u64 v[230:231], v[230:231], 0, v[226:227]
	global_store_dwordx4 v[230:231], v[104:107], off nt
	v_mul_f32_e32 v216, 0xbfb8aa3b, v145
	v_mul_f32_e32 v218, v145, v145
	v_pk_mul_f32 v[194:195], v[92:93], v[216:217] op_sel_hi:[1,0]
	v_pk_mul_f32 v[196:197], v[94:95], v[216:217] op_sel_hi:[1,0]
; __device__ __forceinline__ unsigned cvt_pk_bf16(float lo, float hi) { unsigned r; asm volatile("v_cvt_pk_bf16_f32 %0, %1, %2" : "=v"(r) : "v"(lo), "v"(hi)); return r; }
;     __device__ __forceinline__ void operator()(const f32x4 (&acc)[2][2][4][2], const Unit& u, int wr, int wc, int fr, int fq) const {
;     ...
;             for (int m = 0; m < 4; ++m) { const int row = row0 + ai * HALF + m * 16; const float rs = rsv[ai][m], c1 = rs * -1.4426950408889634f, rs2 = rs * rs;
;                 u32x4 w;
; #pragma unroll
;                 for (int n = 0; n < 2; ++n)
; #pragma unroll
;                     for (int h = 0; h < 2; ++h) { const f32x2 g = (f32x2){acc[ai][0][m][n][2 * h], acc[ai][0][m][n][2 * h + 1]}, up = (f32x2){acc[ai][1][m][n][2 * h], acc[ai][1][m][n][2 * h + 1]};
;                         const f32x2 t = g * c1; f32x2 d = (f32x2){__builtin_amdgcn_exp2f(t[0]), __builtin_amdgcn_exp2f(t[1])} + 1.0f;
;                         const f32x2 r = (f32x2){__builtin_amdgcn_rcpf(d[0]), __builtin_amdgcn_rcpf(d[1])}; const f32x2 o = (g * up) * (r * rs2);
;                         w[2 * n + h] = cvt_pk_bf16(o[0], o[1]); }
;                 __builtin_nontemporal_store(w, (u32x4*)(H + (size_t)row * ldh + col0)); }
	v_pk_mul_f32 v[198:199], v[80:81], v[216:217] op_sel_hi:[1,0]
	v_pk_mul_f32 v[200:201], v[82:83], v[216:217] op_sel_hi:[1,0]
	v_pk_mul_f32 v[84:85], v[80:81], v[84:85]
	v_exp_f32_e32 v194, v194
	v_exp_f32_e32 v195, v195
	v_exp_f32_e32 v196, v196
	v_exp_f32_e32 v197, v197
	v_exp_f32_e32 v198, v198
	v_exp_f32_e32 v199, v199
	v_exp_f32_e32 v200, v200
	v_exp_f32_e32 v201, v201
	v_pk_add_f32 v[194:195], v[194:195], 1.0 op_sel_hi:[1,0]
	v_pk_add_f32 v[196:197], v[196:197], 1.0 op_sel_hi:[1,0]
	v_pk_add_f32 v[198:199], v[198:199], 1.0 op_sel_hi:[1,0]
	v_pk_add_f32 v[200:201], v[200:201], 1.0 op_sel_hi:[1,0]
	v_rcp_f32_e32 v194, v194
	v_rcp_f32_e32 v195, v195
	v_rcp_f32_e32 v196, v196
	v_rcp_f32_e32 v197, v197
	v_rcp_f32_e32 v198, v198
	v_rcp_f32_e32 v199, v199
	v_rcp_f32_e32 v200, v200
	v_rcp_f32_e32 v201, v201
	v_pk_mul_f32 v[194:195], v[218:219], v[194:195] op_sel_hi:[0,1]
	v_pk_mul_f32 v[196:197], v[218:219], v[196:197] op_sel_hi:[0,1]
	v_pk_mul_f32 v[198:199], v[218:219], v[198:199] op_sel_hi:[0,1]
	v_pk_mul_f32 v[200:201], v[218:219], v[200:201] op_sel_hi:[0,1]
	v_pk_mul_f32 v[88:89], v[88:89], v[194:195]
	v_pk_mul_f32 v[90:91], v[90:91], v[196:197]
	v_pk_mul_f32 v[84:85], v[84:85], v[198:199]
	v_pk_mul_f32 v[86:87], v[86:87], v[200:201]
	v_mad_i64_i32 v[230:231], s[6:7], v174, s25, v[224:225]
	v_cvt_pk_bf16_f32 v88, v88, v89
	v_cvt_pk_bf16_f32 v89, v90, v91
	v_cvt_pk_bf16_f32 v90, v84, v85
	v_cvt_pk_bf16_f32 v91, v86, v87
	v_lshl_add_u64 v[230:231], v[230:231], 0, v[226:227]
	global_store_dwordx4 v[230:231], v[88:91], off nt
	v_mul_f32_e32 v216, 0xbfb8aa3b, v144
	v_mul_f32_e32 v218, v144, v144
	v_pk_mul_f32 v[194:195], v[76:77], v[216:217] op_sel_hi:[1,0]
	v_pk_mul_f32 v[196:197], v[78:79], v[216:217] op_sel_hi:[1,0]
	v_pk_mul_f32 v[198:199], v[64:65], v[216:217] op_sel_hi:[1,0]
	v_pk_mul_f32 v[200:201], v[66:67], v[216:217] op_sel_hi:[1,0]
	v_pk_mul_f32 v[68:69], v[64:65], v[68:69]
	v_exp_f32_e32 v194, v194
	v_exp_f32_e32 v195, v195
	v_exp_f32_e32 v196, v196
	v_exp_f32_e32 v197, v197
	v_exp_f32_e32 v198, v198
	v_exp_f32_e32 v199, v199
	v_exp_f32_e32 v200, v200
	v_exp_f32_e32 v201, v201
	v_pk_add_f32 v[194:195], v[194:195], 1.0 op_sel_hi:[1,0]
	v_pk_add_f32 v[196:197], v[196:197], 1.0 op_sel_hi:[1,0]
	v_pk_add_f32 v[198:199], v[198:199], 1.0 op_sel_hi:[1,0]
	v_pk_add_f32 v[200:201], v[200:201], 1.0 op_sel_hi:[1,0]
	v_rcp_f32_e32 v194, v194
	v_rcp_f32_e32 v195, v195
	v_rcp_f32_e32 v196, v196
	v_rcp_f32_e32 v197, v197
	v_rcp_f32_e32 v198, v198
	v_rcp_f32_e32 v199, v199
	v_rcp_f32_e32 v200, v200
	v_rcp_f32_e32 v201, v201
	v_pk_mul_f32 v[194:195], v[218:219], v[194:195] op_sel_hi:[0,1]
	v_pk_mul_f32 v[196:197], v[218:219], v[196:197] op_sel_hi:[0,1]
	v_pk_mul_f32 v[198:199], v[218:219], v[198:199] op_sel_hi:[0,1]
	v_pk_mul_f32 v[200:201], v[218:219], v[200:201] op_sel_hi:[0,1]
	v_pk_mul_f32 v[72:73], v[72:73], v[194:195]
	v_pk_mul_f32 v[74:75], v[74:75], v[196:197]
	v_pk_mul_f32 v[68:69], v[68:69], v[198:199]
	v_pk_mul_f32 v[70:71], v[70:71], v[200:201]
	v_mad_i64_i32 v[230:231], s[6:7], v172, s25, v[224:225]
	v_cvt_pk_bf16_f32 v72, v72, v73
	v_cvt_pk_bf16_f32 v73, v74, v75
	v_cvt_pk_bf16_f32 v74, v68, v69
	v_cvt_pk_bf16_f32 v75, v70, v71
	v_lshl_add_u64 v[230:231], v[230:231], 0, v[226:227]
	global_store_dwordx4 v[230:231], v[72:75], off nt
	v_mul_f32_e32 v216, 0xbfb8aa3b, v137
	v_mul_f32_e32 v218, v137, v137
	v_pk_mul_f32 v[194:195], v[60:61], v[216:217] op_sel_hi:[1,0]
	v_pk_mul_f32 v[196:197], v[62:63], v[216:217] op_sel_hi:[1,0]
	v_pk_mul_f32 v[198:199], v[48:49], v[216:217] op_sel_hi:[1,0]
	v_pk_mul_f32 v[200:201], v[50:51], v[216:217] op_sel_hi:[1,0]
	v_pk_mul_f32 v[52:53], v[48:49], v[52:53]
	v_exp_f32_e32 v194, v194
	v_exp_f32_e32 v195, v195
	v_exp_f32_e32 v196, v196
	v_exp_f32_e32 v197, v197
	v_exp_f32_e32 v198, v198
	v_exp_f32_e32 v199, v199
	v_exp_f32_e32 v200, v200
	v_exp_f32_e32 v201, v201
	v_pk_add_f32 v[194:195], v[194:195], 1.0 op_sel_hi:[1,0]
	v_pk_add_f32 v[196:197], v[196:197], 1.0 op_sel_hi:[1,0]
	v_pk_add_f32 v[198:199], v[198:199], 1.0 op_sel_hi:[1,0]
	v_pk_add_f32 v[200:201], v[200:201], 1.0 op_sel_hi:[1,0]
	v_rcp_f32_e32 v194, v194
	v_rcp_f32_e32 v195, v195
	v_rcp_f32_e32 v196, v196
	v_rcp_f32_e32 v197, v197
	v_rcp_f32_e32 v198, v198
	v_rcp_f32_e32 v199, v199
	v_rcp_f32_e32 v200, v200
	v_rcp_f32_e32 v201, v201
	v_pk_mul_f32 v[194:195], v[218:219], v[194:195] op_sel_hi:[0,1]
	v_pk_mul_f32 v[196:197], v[218:219], v[196:197] op_sel_hi:[0,1]
	v_pk_mul_f32 v[198:199], v[218:219], v[198:199] op_sel_hi:[0,1]
	v_pk_mul_f32 v[200:201], v[218:219], v[200:201] op_sel_hi:[0,1]
	v_pk_mul_f32 v[56:57], v[56:57], v[194:195]
	v_pk_mul_f32 v[58:59], v[58:59], v[196:197]
	v_pk_mul_f32 v[52:53], v[52:53], v[198:199]
	v_pk_mul_f32 v[54:55], v[54:55], v[200:201]
	v_mad_i64_i32 v[230:231], s[6:7], v170, s25, v[224:225]
	v_cvt_pk_bf16_f32 v56, v56, v57
	v_cvt_pk_bf16_f32 v57, v58, v59
	v_cvt_pk_bf16_f32 v58, v52, v53
	v_cvt_pk_bf16_f32 v59, v54, v55
	v_lshl_add_u64 v[230:231], v[230:231], 0, v[226:227]
	global_store_dwordx4 v[230:231], v[56:59], off nt
	v_mul_f32_e32 v216, 0xbfb8aa3b, v136
	v_mul_f32_e32 v218, v136, v136
	v_pk_mul_f32 v[194:195], v[44:45], v[216:217] op_sel_hi:[1,0]
; __device__ __forceinline__ unsigned cvt_pk_bf16(float lo, float hi) { unsigned r; asm volatile("v_cvt_pk_bf16_f32 %0, %1, %2" : "=v"(r) : "v"(lo), "v"(hi)); return r; }
; #define PG8_BAR __builtin_amdgcn_s_barrier()
;     __device__ __forceinline__ void operator()(const f32x4 (&acc)[2][2][4][2], const Unit& u, int wr, int wc, int fr, int fq) const {
;     ...
;             for (int m = 0; m < 4; ++m) { const int row = row0 + ai * HALF + m * 16; const float rs = rsv[ai][m], c1 = rs * -1.4426950408889634f, rs2 = rs * rs;
;                 u32x4 w;
; #pragma unroll
;                 for (int n = 0; n < 2; ++n)
; #pragma unroll
;                     for (int h = 0; h < 2; ++h) { const f32x2 g = (f32x2){acc[ai][0][m][n][2 * h], acc[ai][0][m][n][2 * h + 1]}, up = (f32x2){acc[ai][1][m][n][2 * h], acc[ai][1][m][n][2 * h + 1]};
;                         const f32x2 t = g * c1; f32x2 d = (f32x2){__builtin_amdgcn_exp2f(t[0]), __builtin_amdgcn_exp2f(t[1])} + 1.0f;
;                         const f32x2 r = (f32x2){__builtin_amdgcn_rcpf(d[0]), __builtin_amdgcn_rcpf(d[1])}; const f32x2 o = (g * up) * (r * rs2);
;                         w[2 * n + h] = cvt_pk_bf16(o[0], o[1]); }
;                 __builtin_nontemporal_store(w, (u32x4*)(H + (size_t)row * ldh + col0)); }
; template <class Epi, class Sched, bool ALIGN_EPI = false, bool SP2 = false>
; __device__ __forceinline__ void gemm_phase(PG8_LAS unsigned char* lds, const Gemm g, const Sched& S, const Epi& E) {
;     ...
;         if (!has_next) break;
; #pragma unroll
;         for (int a = 0; a < 2; ++a)
; #pragma unroll
;             for (int b = 0; b < 2; ++b)
; #pragma unroll
;                 for (int m = 0; m < 4; ++m)
; #pragma unroll
;                     for (int n = 0; n < 2; ++n) acc[a][b][m][n] = (f32x4){0.f, 0.f, 0.f, 0.f};
;         cur = nxt; cA = nA; cB = nB; ++ui;
;         if constexpr (ALIGN_EPI) { if (wr == 1) PG8_BAR; }
	v_pk_mul_f32 v[196:197], v[46:47], v[216:217] op_sel_hi:[1,0]
	v_pk_mul_f32 v[198:199], v[32:33], v[216:217] op_sel_hi:[1,0]
	v_pk_mul_f32 v[200:201], v[34:35], v[216:217] op_sel_hi:[1,0]
	v_pk_mul_f32 v[36:37], v[32:33], v[36:37]
	v_exp_f32_e32 v194, v194
	v_exp_f32_e32 v195, v195
	v_exp_f32_e32 v196, v196
	v_exp_f32_e32 v197, v197
	v_exp_f32_e32 v198, v198
	v_exp_f32_e32 v199, v199
	v_exp_f32_e32 v200, v200
	v_exp_f32_e32 v201, v201
	v_pk_add_f32 v[194:195], v[194:195], 1.0 op_sel_hi:[1,0]
	v_pk_add_f32 v[196:197], v[196:197], 1.0 op_sel_hi:[1,0]
	v_pk_add_f32 v[198:199], v[198:199], 1.0 op_sel_hi:[1,0]
	v_pk_add_f32 v[200:201], v[200:201], 1.0 op_sel_hi:[1,0]
	v_rcp_f32_e32 v194, v194
	v_rcp_f32_e32 v195, v195
	v_rcp_f32_e32 v196, v196
	v_rcp_f32_e32 v197, v197
	v_rcp_f32_e32 v198, v198
	v_rcp_f32_e32 v199, v199
	v_rcp_f32_e32 v200, v200
	v_rcp_f32_e32 v201, v201
	v_pk_mul_f32 v[194:195], v[218:219], v[194:195] op_sel_hi:[0,1]
	v_pk_mul_f32 v[196:197], v[218:219], v[196:197] op_sel_hi:[0,1]
	v_pk_mul_f32 v[198:199], v[218:219], v[198:199] op_sel_hi:[0,1]
	v_pk_mul_f32 v[200:201], v[218:219], v[200:201] op_sel_hi:[0,1]
	v_pk_mul_f32 v[40:41], v[40:41], v[194:195]
	v_pk_mul_f32 v[42:43], v[42:43], v[196:197]
	v_pk_mul_f32 v[36:37], v[36:37], v[198:199]
	v_pk_mul_f32 v[38:39], v[38:39], v[200:201]
	v_mad_i64_i32 v[230:231], s[6:7], v168, s25, v[224:225]
	v_cvt_pk_bf16_f32 v40, v40, v41
	v_cvt_pk_bf16_f32 v41, v42, v43
	v_cvt_pk_bf16_f32 v42, v36, v37
	v_cvt_pk_bf16_f32 v43, v38, v39
	v_lshl_add_u64 v[230:231], v[230:231], 0, v[226:227]
	global_store_dwordx4 v[230:231], v[40:43], off nt
	v_mul_f32_e32 v216, 0xbfb8aa3b, v129
	v_mul_f32_e32 v218, v129, v129
	v_pk_mul_f32 v[194:195], v[28:29], v[216:217] op_sel_hi:[1,0]
	v_pk_mul_f32 v[196:197], v[30:31], v[216:217] op_sel_hi:[1,0]
	v_pk_mul_f32 v[198:199], v[16:17], v[216:217] op_sel_hi:[1,0]
	v_pk_mul_f32 v[200:201], v[18:19], v[216:217] op_sel_hi:[1,0]
	v_pk_mul_f32 v[20:21], v[16:17], v[20:21]
	v_exp_f32_e32 v194, v194
	v_exp_f32_e32 v195, v195
	v_exp_f32_e32 v196, v196
	v_exp_f32_e32 v197, v197
	v_exp_f32_e32 v198, v198
	v_exp_f32_e32 v199, v199
	v_exp_f32_e32 v200, v200
	v_exp_f32_e32 v201, v201
	v_pk_add_f32 v[194:195], v[194:195], 1.0 op_sel_hi:[1,0]
	v_pk_add_f32 v[196:197], v[196:197], 1.0 op_sel_hi:[1,0]
	v_pk_add_f32 v[198:199], v[198:199], 1.0 op_sel_hi:[1,0]
	v_pk_add_f32 v[200:201], v[200:201], 1.0 op_sel_hi:[1,0]
	v_rcp_f32_e32 v194, v194
	v_rcp_f32_e32 v195, v195
	v_rcp_f32_e32 v196, v196
	v_rcp_f32_e32 v197, v197
	v_rcp_f32_e32 v198, v198
	v_rcp_f32_e32 v199, v199
	v_rcp_f32_e32 v200, v200
	v_rcp_f32_e32 v201, v201
	v_pk_mul_f32 v[194:195], v[218:219], v[194:195] op_sel_hi:[0,1]
	v_pk_mul_f32 v[196:197], v[218:219], v[196:197] op_sel_hi:[0,1]
	v_pk_mul_f32 v[198:199], v[218:219], v[198:199] op_sel_hi:[0,1]
	v_pk_mul_f32 v[200:201], v[218:219], v[200:201] op_sel_hi:[0,1]
	v_pk_mul_f32 v[24:25], v[24:25], v[194:195]
	v_pk_mul_f32 v[26:27], v[26:27], v[196:197]
	v_pk_mul_f32 v[20:21], v[20:21], v[198:199]
	v_pk_mul_f32 v[22:23], v[22:23], v[200:201]
	v_mad_i64_i32 v[230:231], s[6:7], v166, s25, v[224:225]
	v_cvt_pk_bf16_f32 v24, v24, v25
	v_cvt_pk_bf16_f32 v25, v26, v27
	v_cvt_pk_bf16_f32 v26, v20, v21
	v_cvt_pk_bf16_f32 v27, v22, v23
	v_lshl_add_u64 v[230:231], v[230:231], 0, v[226:227]
	global_store_dwordx4 v[230:231], v[24:27], off nt
	v_mul_f32_e32 v216, 0xbfb8aa3b, v128
	v_mul_f32_e32 v218, v128, v128
	v_pk_mul_f32 v[194:195], v[12:13], v[216:217] op_sel_hi:[1,0]
	v_pk_mul_f32 v[196:197], v[14:15], v[216:217] op_sel_hi:[1,0]
	v_pk_mul_f32 v[198:199], v[4:5], v[216:217] op_sel_hi:[1,0]
	v_pk_mul_f32 v[200:201], v[6:7], v[216:217] op_sel_hi:[1,0]
	v_exp_f32_e32 v194, v194
	v_exp_f32_e32 v195, v195
	v_exp_f32_e32 v196, v196
	v_exp_f32_e32 v197, v197
	v_exp_f32_e32 v198, v198
	v_exp_f32_e32 v199, v199
	v_exp_f32_e32 v200, v200
	v_exp_f32_e32 v201, v201
	v_pk_add_f32 v[194:195], v[194:195], 1.0 op_sel_hi:[1,0]
	v_pk_add_f32 v[196:197], v[196:197], 1.0 op_sel_hi:[1,0]
	v_pk_add_f32 v[198:199], v[198:199], 1.0 op_sel_hi:[1,0]
	v_pk_add_f32 v[200:201], v[200:201], 1.0 op_sel_hi:[1,0]
	v_rcp_f32_e32 v194, v194
	v_rcp_f32_e32 v195, v195
	v_rcp_f32_e32 v196, v196
	v_rcp_f32_e32 v197, v197
	v_rcp_f32_e32 v198, v198
	v_rcp_f32_e32 v199, v199
	v_rcp_f32_e32 v200, v200
	v_rcp_f32_e32 v201, v201
	v_pk_mul_f32 v[194:195], v[218:219], v[194:195] op_sel_hi:[0,1]
	v_pk_mul_f32 v[196:197], v[218:219], v[196:197] op_sel_hi:[0,1]
	v_pk_mul_f32 v[198:199], v[218:219], v[198:199] op_sel_hi:[0,1]
	v_pk_mul_f32 v[200:201], v[218:219], v[200:201] op_sel_hi:[0,1]
	v_pk_mul_f32 v[8:9], v[8:9], v[194:195]
	v_pk_mul_f32 v[10:11], v[10:11], v[196:197]
	v_pk_mul_f32 v[0:1], v[0:1], v[198:199]
	v_pk_mul_f32 v[2:3], v[2:3], v[200:201]
	v_mad_i64_i32 v[230:231], s[6:7], v164, s25, v[224:225]
	v_cvt_pk_bf16_f32 v8, v8, v9
	v_cvt_pk_bf16_f32 v9, v10, v11
	v_cvt_pk_bf16_f32 v10, v0, v1
	v_cvt_pk_bf16_f32 v11, v2, v3
	v_lshl_add_u64 v[230:231], v[230:231], 0, v[226:227]
	s_mov_b64 s[6:7], -1
	global_store_dwordx4 v[230:231], v[8:11], off nt
	s_cbranch_vccnz .LBB0_194
	s_andn2_b64 vcc, exec, s[8:9]
	s_cbranch_vccnz .LBB0_193
	s_barrier
	s_branch .LBB0_193
